# variant: static priority 3 (instead of 1) for waves 4-7 during prompt attention
# speedup vs baseline: 1.0083x; 1.0043x over previous
; #define LAS __attribute__((address_space(3)))
; __device__ __forceinline__ Grp make_grp(const Args& a, int g) {
;     Grp G; unsigned char* base; size_t RC;
;     if (g == 0) {
;         G.x = a.in[1]; G.y = a.out + O_YS; G.okd = a.out + O_KDS; G.ovd = a.out + O_VDS; G.ockv = a.out + O_CKVS; G.okr = a.out + O_KRS;
;         G.nvalid = SB * ST; G.ntiles = 1; G.sample = 1; base = a.ws + WS_SAMP; RC = 256;
;     } else {
;         const size_t r0 = (size_t)(g - 1) * RG;
; __device__ __forceinline__ void phase_attention(const Args& a, const Grp& G, LAS unsigned char* lds, const int tid_in) {
;     int tid_ = tid_in; asm volatile("" : "+v"(tid_));
;     const int tid = tid_, lane = tid & 63, wid = __builtin_amdgcn_readfirstlane(tid >> 6);
;     const float* tabg = (const float*)(a.ws + WS_TAB);
;     for (int i = tid; i < 8 * 192; i += 512) ((LAS float*)(lds + AL_TAB))[i] = tabg[i];
;     const float lam = tabg[1536];
;     const float* subln = a.in[13];
;     __syncthreads();
;     if (G.sample) {
;         if (wid < 4) {
;             constexpr int TBD = 64 * (64 * 2 + 16) + 64 * (128 * 2 + 64);
;             LAS unsigned char* wt = lds + AL_TILE + wid * TBD;
;             LAS float* wsf = (LAS float*)(lds + AL_WSF) + wid * 64;
;             const LAS float* tab0 = (const LAS float*)(lds + AL_TAB);
;             const unsigned char* cb = a.ws + WS_CACHE;
;             for (int wu = (int)blockIdx.x * 4 + wid; wu < 1024; wu += (int)gridDim.x * 4) {
;                 const int s = wu & 3; const int j0 = s == 0 ? 0 : 17 + 16 * (s - 1), j1 = 17 + 16 * s;
;                 if (wu < 512) {
;     ...
;  const int n = (wu >> 2) & 1, h = (wu >> 3) & 7, b = wu >> 6;
;                     attn_unit_wave<true>(G, cb, b, h, n, j0, j1, wu, (float*)(a.ws + WS_PO_D), (float*)(a.ws + WS_PM), (float*)(a.ws + WS_PL), wt, wsf, tab0, tid);
;     ...
;                 } else {
;     ...
;  const int i2 = wu - 512; const int h = (i2 >> 2) & 15, b = i2 >> 6;
;                     attn_unit_wave<false>(G, cb, b, h, 0, j0, j1, wu, (float*)(a.ws + WS_PO_M) - (size_t)512 * 32 * 64, (float*)(a.ws + WS_PM), (float*)(a.ws + WS_PL), wt, wsf, tab0, tid);
;     ...
;                 }
;             }
;         }
;     } else {
;         const int Gn = (int)gridDim.x, bx = (int)blockIdx.x;
;         const int vcu = (Gn % 8 == 0) ? (bx % 8) * (Gn / 8) + bx / 8 : bx;
;         for (int v = vcu; v < 256; v += Gn) {
.LBB0_510:
	s_or_b64 exec, exec, s[0:1]
	global_load_dword v192, v204, s[18:19] offset:2048
	s_cmp_eq_u32 s6, 0
	s_cselect_b64 s[0:1], -1, 0
	s_and_b64 s[2:3], s[0:1], exec
	s_mov_b32 s2, 0x2500000
	s_mov_b32 s3, 0x280000
	s_cselect_b32 s10, s2, 0x3a00000
	s_mov_b32 s2, 0x8000
	s_cselect_b32 s4, s3, 0x14000000
	s_mov_b32 s3, 0x300000
	s_cselect_b32 s13, 0x100, s2
	s_mov_b32 s2, 0x180000
	s_cselect_b32 s5, s3, 0x18000000
	s_mov_b32 s3, 0x500000
	s_mov_b32 s7, 0x540000
	s_cselect_b32 s2, s2, 0xc000000
	s_cselect_b32 s3, s3, 0x28000000
	s_cselect_b32 s7, s7, 0x2a000000
	s_add_u32 s14, s18, s10
	s_addc_u32 s15, s19, 0
	s_lshl_b32 s12, s13, 11
	s_add_u32 s16, s14, s12
	s_addc_u32 s17, s15, 0
	s_waitcnt vmcnt(0) lgkmcnt(0)
	v_writelane_b32 v246, s16, 0
	s_add_u32 s16, s16, s12
	v_writelane_b32 v246, s16, 1
	v_writelane_b32 v246, s17, 2
	s_addc_u32 s16, s17, 0
	v_writelane_b32 v246, s16, 3
	s_add_u32 s16, s14, s2
	s_addc_u32 s17, s15, 0
	v_writelane_b32 v246, s16, 4
	s_add_u32 s2, s14, s4
	s_barrier
	v_writelane_b32 v246, s17, 5
	v_writelane_b32 v246, s2, 6
	s_addc_u32 s2, s15, 0
	v_writelane_b32 v246, s2, 7
	s_add_u32 s2, s14, s5
	v_writelane_b32 v246, s2, 8
	s_addc_u32 s2, s15, 0
	v_writelane_b32 v246, s2, 9
	s_add_u32 s2, s14, s3
	s_addc_u32 s3, s15, 0
	v_writelane_b32 v246, s2, 10
	s_add_u32 s70, s14, s7
	s_addc_u32 s71, s15, 0
	v_writelane_b32 v246, s3, 11
	v_writelane_b32 v246, s14, 12
	s_cmp_lg_u32 s6, 0
	s_mov_b64 s[2:3], -1
	v_writelane_b32 v246, s15, 13
	s_cbranch_scc0 .LBB0_605
	v_readlane_b32 s2, v247, 11
	v_writelane_b32 v246, s20, 22
	v_readlane_b32 s3, v247, 12
	v_writelane_b32 v246, s18, 20
	s_andn2_b64 vcc, exec, s[2:3]
	s_nop 0
	v_writelane_b32 v246, s19, 21
	s_cbranch_vccnz .LBB0_604
	v_readlane_b32 s98, v247, 43
	s_cmp_lt_u32 s98, 4
	s_cbranch_scc1 .Lprio_skip
	s_setprio 3
